# attention prompt items: all six K/V staging loads issued before the LDS writes (one exposed latency instead of six); rest as previous best
# baseline (speedup 1.0000x reference)
; __device__ __forceinline__ unsigned cvt_pk_bf16(float lo, float hi) { const f32x2_cv v = {lo, hi}; return __builtin_bit_cast(unsigned, __builtin_convertvector(v, bf16x2_cv)); }
; __device__ __forceinline__ void attn_item(const bf16_t* Z, const float* ck, const float* cv, const float* btab, const float* sinks, bf16_t* MIX, int item, LAS unsigned char* lds, int tid, int wave, int lane) {
;     ...
;     for (int it = 0; it < 6; ++it) {
;         const int task = tid + NTHR * it, kq = task & 3, key = (task >> 2) % 192, ch = (task / 768) * 4 + kq;
;         u32x4 kv4 = {0u, 0u, 0u, 0u}, vv4 = {0u, 0u, 0u, 0u};
;         if (!prompt && key < 128) {
;             const float* kp = ck + ((size_t)(sidx * 128 + key) * 2 + kvh) * 128 + ch * 8; const float* vp = cv + ((size_t)(sidx * 128 + key) * 2 + kvh) * 128 + ch * 8;
;             const f32x4 a = *(const f32x4*)kp, b = *(const f32x4*)(kp + 4), c = *(const f32x4*)vp, d = *(const f32x4*)(vp + 4);
;             kv4 = (u32x4){cvt_pk_bf16(a.x, a.y), cvt_pk_bf16(a.z, a.w), cvt_pk_bf16(b.x, b.y), cvt_pk_bf16(b.z, b.w)};
;             vv4 = (u32x4){cvt_pk_bf16(c.x, c.y), cvt_pk_bf16(c.z, c.w), cvt_pk_bf16(d.x, d.y), cvt_pk_bf16(d.z, d.w)};
;         } else if (key >= kmin) {
;             const bf16_t* zp = Z + (size_t)(krow0 + key) * DIN + ZK + kvh * 128 + ch * 8;
;             kv4 = *(const u32x4*)zp; vv4 = *(const u32x4*)(zp + 256);
;         }
.LBB0_579:
	s_and_b32 s14, s79, 1
	s_lshl_b32 s6, s14, 8
	s_add_u32 s6, s68, s6
	v_add_u32_e32 v0, 0x200, v8
	v_and_b32_e32 v9, 3, v8
	s_addc_u32 s7, s69, 0
	v_lshrrev_b32_e32 v10, 2, v0
	v_lshrrev_b32_e32 v11, 2, v8
	s_xor_b64 s[8:9], s[8:9], -1
	v_mov_b32_e32 v12, v8
	s_and_b64 vcc, exec, s[8:9]
	s_cbranch_vccz .LBB0_581
	v_mov_b32_e32 v0, v8
	v_lshrrev_b32_e32 v1, 2, v0
	v_mul_u32_u24_e32 v2, 0xaaab, v1
	v_lshrrev_b32_e32 v2, 23, v2
	v_mul_lo_u16_e32 v2, 0xc0, v2
	v_sub_u16_e32 v212, v1, v2
	v_mul_u32_u24_e32 v3, 0xaaab, v0
	v_lshrrev_b32_e32 v3, 23, v3
	v_and_or_b32 v218, v3, s72, v9
	v_mov_b32_e32 v164, 0
	v_mov_b32_e32 v165, 0
	v_mov_b32_e32 v166, 0
	v_mov_b32_e32 v167, 0
	v_mov_b32_e32 v168, 0
	v_mov_b32_e32 v169, 0
	v_mov_b32_e32 v170, 0
	v_mov_b32_e32 v171, 0
	v_cmp_le_i32_e32 vcc, s66, v212
	s_and_saveexec_b64 s[12:13], vcc
	s_cbranch_execz .Lat_skip0
	v_add_u32_e32 v2, s15, v212
	v_mov_b64_e32 v[0:1], s[6:7]
	v_mad_i64_i32 v[0:1], s[18:19], v2, s74, v[0:1]
	v_lshlrev_b32_e32 v120, 4, v218
	v_lshl_add_u64 v[224:225], v[0:1], 0, v[120:121]
	global_load_dwordx4 v[164:167], v[224:225], off offset:2048
	global_load_dwordx4 v[168:171], v[224:225], off offset:2560
.Lat_skip0:
	s_or_b64 exec, exec, s[12:13]
	v_add_u32_e32 v0, 0x200, v8
	v_lshrrev_b32_e32 v1, 2, v0
	v_mul_u32_u24_e32 v2, 0xaaab, v1
	v_lshrrev_b32_e32 v2, 23, v2
	v_mul_lo_u16_e32 v2, 0xc0, v2
	v_sub_u16_e32 v213, v1, v2
	v_mul_u32_u24_e32 v3, 0xaaab, v0
	v_lshrrev_b32_e32 v3, 23, v3
	v_and_or_b32 v219, v3, s72, v9
	v_mov_b32_e32 v172, 0
	v_mov_b32_e32 v173, 0
	v_mov_b32_e32 v174, 0
	v_mov_b32_e32 v175, 0
	v_mov_b32_e32 v176, 0
	v_mov_b32_e32 v177, 0
	v_mov_b32_e32 v178, 0
	v_mov_b32_e32 v179, 0
	v_cmp_le_i32_e32 vcc, s66, v213
	s_and_saveexec_b64 s[12:13], vcc
	s_cbranch_execz .Lat_skip1
	v_add_u32_e32 v2, s15, v213
	v_mov_b64_e32 v[0:1], s[6:7]
	v_mad_i64_i32 v[0:1], s[18:19], v2, s74, v[0:1]
	v_lshlrev_b32_e32 v120, 4, v219
	v_lshl_add_u64 v[224:225], v[0:1], 0, v[120:121]
	global_load_dwordx4 v[172:175], v[224:225], off offset:2048
	global_load_dwordx4 v[176:179], v[224:225], off offset:2560
.Lat_skip1:
	s_or_b64 exec, exec, s[12:13]
	v_add_u32_e32 v0, 0x400, v8
	v_lshrrev_b32_e32 v1, 2, v0
	v_mul_u32_u24_e32 v2, 0xaaab, v1
	v_lshrrev_b32_e32 v2, 23, v2
	v_mul_lo_u16_e32 v2, 0xc0, v2
	v_sub_u16_e32 v214, v1, v2
	v_mul_u32_u24_e32 v3, 0xaaab, v0
	v_lshrrev_b32_e32 v3, 23, v3
	v_and_or_b32 v220, v3, s72, v9
	v_mov_b32_e32 v180, 0
	v_mov_b32_e32 v181, 0
	v_mov_b32_e32 v182, 0
	v_mov_b32_e32 v183, 0
	v_mov_b32_e32 v184, 0
	v_mov_b32_e32 v185, 0
	v_mov_b32_e32 v186, 0
	v_mov_b32_e32 v187, 0
	v_cmp_le_i32_e32 vcc, s66, v214
	s_and_saveexec_b64 s[12:13], vcc
	s_cbranch_execz .Lat_skip2
	v_add_u32_e32 v2, s15, v214
	v_mov_b64_e32 v[0:1], s[6:7]
	v_mad_i64_i32 v[0:1], s[18:19], v2, s74, v[0:1]
	v_lshlrev_b32_e32 v120, 4, v220
	v_lshl_add_u64 v[224:225], v[0:1], 0, v[120:121]
	global_load_dwordx4 v[180:183], v[224:225], off offset:2048
	global_load_dwordx4 v[184:187], v[224:225], off offset:2560
.Lat_skip2:
	s_or_b64 exec, exec, s[12:13]
	v_add_u32_e32 v0, 0x600, v8
	v_lshrrev_b32_e32 v1, 2, v0
	v_mul_u32_u24_e32 v2, 0xaaab, v1
	v_lshrrev_b32_e32 v2, 23, v2
	v_mul_lo_u16_e32 v2, 0xc0, v2
	v_sub_u16_e32 v215, v1, v2
	v_mul_u32_u24_e32 v3, 0xaaab, v0
	v_lshrrev_b32_e32 v3, 23, v3
	v_and_or_b32 v221, v3, s72, v9
	v_mov_b32_e32 v188, 0
	v_mov_b32_e32 v189, 0
	v_mov_b32_e32 v190, 0
	v_mov_b32_e32 v191, 0
	v_mov_b32_e32 v192, 0
	v_mov_b32_e32 v193, 0
	v_mov_b32_e32 v194, 0
	v_mov_b32_e32 v195, 0
	v_cmp_le_i32_e32 vcc, s66, v215
	s_and_saveexec_b64 s[12:13], vcc
	s_cbranch_execz .Lat_skip3
	v_add_u32_e32 v2, s15, v215
	v_mov_b64_e32 v[0:1], s[6:7]
	v_mad_i64_i32 v[0:1], s[18:19], v2, s74, v[0:1]
	v_lshlrev_b32_e32 v120, 4, v221
	v_lshl_add_u64 v[224:225], v[0:1], 0, v[120:121]
	global_load_dwordx4 v[188:191], v[224:225], off offset:2048
	global_load_dwordx4 v[192:195], v[224:225], off offset:2560
.Lat_skip3:
	s_or_b64 exec, exec, s[12:13]
	v_add_u32_e32 v0, 0x800, v8
	v_lshrrev_b32_e32 v1, 2, v0
	v_mul_u32_u24_e32 v2, 0xaaab, v1
	v_lshrrev_b32_e32 v2, 23, v2
	v_mul_lo_u16_e32 v2, 0xc0, v2
	v_sub_u16_e32 v216, v1, v2
	v_mul_u32_u24_e32 v3, 0xaaab, v0
	v_lshrrev_b32_e32 v3, 23, v3
	v_and_or_b32 v222, v3, s72, v9
	v_mov_b32_e32 v196, 0
	v_mov_b32_e32 v197, 0
	v_mov_b32_e32 v198, 0
	v_mov_b32_e32 v199, 0
	v_mov_b32_e32 v200, 0
	v_mov_b32_e32 v201, 0
	v_mov_b32_e32 v202, 0
	v_mov_b32_e32 v203, 0
	v_cmp_le_i32_e32 vcc, s66, v216
	s_and_saveexec_b64 s[12:13], vcc
	s_cbranch_execz .Lat_skip4
	v_add_u32_e32 v2, s15, v216
	v_mov_b64_e32 v[0:1], s[6:7]
	v_mad_i64_i32 v[0:1], s[18:19], v2, s74, v[0:1]
	v_lshlrev_b32_e32 v120, 4, v222
	v_lshl_add_u64 v[224:225], v[0:1], 0, v[120:121]
	global_load_dwordx4 v[196:199], v[224:225], off offset:2048
	global_load_dwordx4 v[200:203], v[224:225], off offset:2560
; #define LAS __attribute__((address_space(3)))
; __device__ __forceinline__ void attn_item(const bf16_t* Z, const float* ck, const float* cv, const float* btab, const float* sinks, bf16_t* MIX, int item, LAS unsigned char* lds, int tid, int wave, int lane) {
;     ...
;         } else if (key >= kmin) {
;             const bf16_t* zp = Z + (size_t)(krow0 + key) * DIN + ZK + kvh * 128 + ch * 8;
;             kv4 = *(const u32x4*)zp; vv4 = *(const u32x4*)(zp + 256);
;         }
;         *(LAS u32x4*)(Ks + key * KS_STRIDE + ch * 8) = kv4;
;         LAS bf16_t* vt = VTs + (ch * 8) * VT_STRIDE + key;
;         vt[0 * VT_STRIDE] = (bf16_t)(vv4.x & 0xffffu); vt[1 * VT_STRIDE] = (bf16_t)(vv4.x >> 16); vt[2 * VT_STRIDE] = (bf16_t)(vv4.y & 0xffffu); vt[3 * VT_STRIDE] = (bf16_t)(vv4.y >> 16);
;         vt[4 * VT_STRIDE] = (bf16_t)(vv4.z & 0xffffu); vt[5 * VT_STRIDE] = (bf16_t)(vv4.z >> 16); vt[6 * VT_STRIDE] = (bf16_t)(vv4.w & 0xffffu); vt[7 * VT_STRIDE] = (bf16_t)(vv4.w >> 16);
;     }
.Lat_skip4:
	s_or_b64 exec, exec, s[12:13]
	v_add_u32_e32 v0, 0xa00, v8
	v_lshrrev_b32_e32 v1, 2, v0
	v_mul_u32_u24_e32 v2, 0xaaab, v1
	v_lshrrev_b32_e32 v2, 23, v2
	v_mul_lo_u16_e32 v2, 0xc0, v2
	v_sub_u16_e32 v217, v1, v2
	v_mul_u32_u24_e32 v3, 0xaaab, v0
	v_lshrrev_b32_e32 v3, 23, v3
	v_and_or_b32 v223, v3, s72, v9
	v_mov_b32_e32 v204, 0
	v_mov_b32_e32 v205, 0
	v_mov_b32_e32 v206, 0
	v_mov_b32_e32 v207, 0
	v_mov_b32_e32 v208, 0
	v_mov_b32_e32 v209, 0
	v_mov_b32_e32 v210, 0
	v_mov_b32_e32 v211, 0
	v_cmp_le_i32_e32 vcc, s66, v217
	s_and_saveexec_b64 s[12:13], vcc
	s_cbranch_execz .Lat_skip5
	v_add_u32_e32 v2, s15, v217
	v_mov_b64_e32 v[0:1], s[6:7]
	v_mad_i64_i32 v[0:1], s[18:19], v2, s74, v[0:1]
	v_lshlrev_b32_e32 v120, 4, v223
	v_lshl_add_u64 v[224:225], v[0:1], 0, v[120:121]
	global_load_dwordx4 v[204:207], v[224:225], off offset:2048
	global_load_dwordx4 v[208:211], v[224:225], off offset:2560
.Lat_skip5:
	s_or_b64 exec, exec, s[12:13]
	s_waitcnt vmcnt(0)
	v_mul_u32_u24_e32 v15, 0x110, v212
	v_lshlrev_b32_e32 v16, 4, v218
	v_add3_u32 v15, 0, v15, v16
	ds_write_b128 v15, v[164:167]
	v_mul_u32_u24_e32 v0, 0xc40, v218
	v_lshlrev_b32_e32 v1, 1, v212
	v_add3_u32 v0, 0, v0, v1
	ds_write_b16 v0, v168 offset:52224
	ds_write_b16_d16_hi v0, v168 offset:52616
	ds_write_b16 v0, v169 offset:53008
	ds_write_b16_d16_hi v0, v169 offset:53400
	ds_write_b16 v0, v170 offset:53792
	ds_write_b16_d16_hi v0, v170 offset:54184
	ds_write_b16 v0, v171 offset:54576
	ds_write_b16_d16_hi v0, v171 offset:54968
	v_mul_u32_u24_e32 v15, 0x110, v213
	v_lshlrev_b32_e32 v16, 4, v219
	v_add3_u32 v15, 0, v15, v16
	ds_write_b128 v15, v[172:175]
	v_mul_u32_u24_e32 v0, 0xc40, v219
	v_lshlrev_b32_e32 v1, 1, v213
	v_add3_u32 v0, 0, v0, v1
	ds_write_b16 v0, v176 offset:52224
	ds_write_b16_d16_hi v0, v176 offset:52616
	ds_write_b16 v0, v177 offset:53008
	ds_write_b16_d16_hi v0, v177 offset:53400
	ds_write_b16 v0, v178 offset:53792
	ds_write_b16_d16_hi v0, v178 offset:54184
	ds_write_b16 v0, v179 offset:54576
	ds_write_b16_d16_hi v0, v179 offset:54968
	v_mul_u32_u24_e32 v15, 0x110, v214
	v_lshlrev_b32_e32 v16, 4, v220
	v_add3_u32 v15, 0, v15, v16
	ds_write_b128 v15, v[180:183]
	v_mul_u32_u24_e32 v0, 0xc40, v220
	v_lshlrev_b32_e32 v1, 1, v214
	v_add3_u32 v0, 0, v0, v1
	ds_write_b16 v0, v184 offset:52224
	ds_write_b16_d16_hi v0, v184 offset:52616
	ds_write_b16 v0, v185 offset:53008
	ds_write_b16_d16_hi v0, v185 offset:53400
	ds_write_b16 v0, v186 offset:53792
	ds_write_b16_d16_hi v0, v186 offset:54184
	ds_write_b16 v0, v187 offset:54576
	ds_write_b16_d16_hi v0, v187 offset:54968
	v_mul_u32_u24_e32 v15, 0x110, v215
	v_lshlrev_b32_e32 v16, 4, v221
	v_add3_u32 v15, 0, v15, v16
	ds_write_b128 v15, v[188:191]
	v_mul_u32_u24_e32 v0, 0xc40, v221
	v_lshlrev_b32_e32 v1, 1, v215
	v_add3_u32 v0, 0, v0, v1
	ds_write_b16 v0, v192 offset:52224
	ds_write_b16_d16_hi v0, v192 offset:52616
	ds_write_b16 v0, v193 offset:53008
	ds_write_b16_d16_hi v0, v193 offset:53400
	ds_write_b16 v0, v194 offset:53792
	ds_write_b16_d16_hi v0, v194 offset:54184
	ds_write_b16 v0, v195 offset:54576
	ds_write_b16_d16_hi v0, v195 offset:54968
	v_mul_u32_u24_e32 v15, 0x110, v216
	v_lshlrev_b32_e32 v16, 4, v222
	v_add3_u32 v15, 0, v15, v16
	ds_write_b128 v15, v[196:199]
	v_mul_u32_u24_e32 v0, 0xc40, v222
	v_lshlrev_b32_e32 v1, 1, v216
	v_add3_u32 v0, 0, v0, v1
	ds_write_b16 v0, v200 offset:52224
	ds_write_b16_d16_hi v0, v200 offset:52616
	ds_write_b16 v0, v201 offset:53008
	ds_write_b16_d16_hi v0, v201 offset:53400
	ds_write_b16 v0, v202 offset:53792
	ds_write_b16_d16_hi v0, v202 offset:54184
	ds_write_b16 v0, v203 offset:54576
	ds_write_b16_d16_hi v0, v203 offset:54968
	v_mul_u32_u24_e32 v15, 0x110, v217
	v_lshlrev_b32_e32 v16, 4, v223
	v_add3_u32 v15, 0, v15, v16
	ds_write_b128 v15, v[204:207]
	v_mul_u32_u24_e32 v0, 0xc40, v223
	v_lshlrev_b32_e32 v1, 1, v217
	v_add3_u32 v0, 0, v0, v1
	ds_write_b16 v0, v208 offset:52224
	ds_write_b16_d16_hi v0, v208 offset:52616
	ds_write_b16 v0, v209 offset:53008
	ds_write_b16_d16_hi v0, v209 offset:53400
	ds_write_b16 v0, v210 offset:53792
	ds_write_b16_d16_hi v0, v210 offset:54184
	ds_write_b16 v0, v211 offset:54576
	ds_write_b16_d16_hi v0, v211 offset:54968
	s_branch .LBB0_641
	s_branch .LBB0_581
